# SwiGLU epilogue H stores issued with the nt (streaming) cache hint
# speedup vs baseline: 1.0208x; 1.0027x over previous
.LBB0_279:
	v_lshl_add_u32 v176, s6, 8, v203
	v_ashrrev_i32_e32 v177, 31, v176
	v_lshlrev_b64 v[76:77], 6, v[176:177]
	v_lshl_add_u64 v[76:77], v[160:161], 0, v[76:77]
	v_or_b32_e32 v184, 16, v176
	global_load_dwordx4 v[168:171], v[76:77], off
	v_ashrrev_i32_e32 v185, 31, v184
	v_lshlrev_b64 v[76:77], 6, v[184:185]
	v_lshl_add_u64 v[76:77], v[160:161], 0, v[76:77]
	global_load_dwordx4 v[208:211], v[76:77], off
	v_or_b32_e32 v182, 32, v176
	v_ashrrev_i32_e32 v183, 31, v182
	v_lshlrev_b64 v[76:77], 6, v[182:183]
	v_or_b32_e32 v180, 48, v176
	v_lshl_add_u64 v[76:77], v[160:161], 0, v[76:77]
	v_ashrrev_i32_e32 v181, 31, v180
	global_load_dwordx4 v[150:153], v[76:77], off
	v_lshlrev_b64 v[76:77], 6, v[180:181]
	v_add_u32_e32 v178, 0x80, v176
	v_lshl_add_u64 v[76:77], v[160:161], 0, v[76:77]
	v_ashrrev_i32_e32 v179, 31, v178
	global_load_dwordx4 v[146:149], v[76:77], off
	v_lshlrev_b64 v[76:77], 6, v[178:179]
	v_add_u32_e32 v174, 0x90, v176
	v_lshl_add_u64 v[76:77], v[160:161], 0, v[76:77]
	v_ashrrev_i32_e32 v175, 31, v174
	global_load_dwordx4 v[122:125], v[76:77], off
	v_lshlrev_b64 v[76:77], 6, v[174:175]
	v_add_u32_e32 v172, 0xa0, v176
	v_lshl_add_u64 v[76:77], v[160:161], 0, v[76:77]
	v_ashrrev_i32_e32 v173, 31, v172
	v_lshl_or_b32 v194, s7, 7, v205
	global_load_dwordx4 v[118:121], v[76:77], off
	v_lshlrev_b64 v[76:77], 6, v[172:173]
	v_add_u32_e32 v166, 0xb0, v176
	v_ashrrev_i32_e32 v195, 31, v194
	v_lshl_add_u64 v[76:77], v[160:161], 0, v[76:77]
	v_ashrrev_i32_e32 v167, 31, v166
	v_and_b32_e32 v173, 64, v245
	global_load_dwordx4 v[80:83], v[76:77], off
	v_lshlrev_b64 v[76:77], 6, v[166:167]
	v_xor_b32_e32 v167, 16, v245
	v_add_u32_e32 v175, 64, v173
	v_cmp_lt_i32_e32 vcc, v167, v175
	s_mov_b32 s22, 0x3a800000
	v_lshl_add_u64 v[76:77], v[160:161], 0, v[76:77]
	v_cndmask_b32_e32 v167, v245, v167, vcc
	v_lshlrev_b32_e32 v173, 2, v167
	v_xor_b32_e32 v167, 32, v245
	v_cmp_lt_i32_e32 vcc, v167, v175
	global_load_dwordx4 v[76:79], v[76:77], off
	v_readlane_b32 s50, v255, 34
	v_cndmask_b32_e32 v167, v245, v167, vcc
	v_lshlrev_b32_e32 v167, 2, v167
	v_readlane_b32 s62, v255, 36
	v_readlane_b32 s51, v255, 35
	v_readlane_b32 s63, v255, 37
	s_waitcnt vmcnt(0)
	v_add_f32_e32 v169, v169, v168
	v_add_f32_e32 v171, v170, v171
	v_add_f32_e32 v209, v209, v208
	v_add_f32_e32 v211, v210, v211
	v_add_f32_e32 v151, v151, v150
	v_add_f32_e32 v153, v152, v153
	v_add_f32_e32 v147, v147, v146
	v_add_f32_e32 v149, v148, v149
	v_add_f32_e32 v123, v123, v122
	v_add_f32_e32 v125, v124, v125
	v_add_f32_e32 v119, v119, v118
	v_add_f32_e32 v121, v120, v121
	v_add_f32_e32 v81, v81, v80
	v_add_f32_e32 v83, v82, v83
	v_add_f32_e32 v77, v77, v76
	v_add_f32_e32 v79, v78, v79
	v_add_f32_e32 v168, v169, v171
	v_add_f32_e32 v208, v209, v211
	v_add_f32_e32 v150, v151, v153
	v_add_f32_e32 v146, v147, v149
	v_add_f32_e32 v122, v123, v125
	v_add_f32_e32 v118, v119, v121
	v_add_f32_e32 v80, v81, v83
	v_add_f32_e32 v76, v77, v79
	ds_bpermute_b32 v169, v173, v168
	ds_bpermute_b32 v209, v173, v208
	ds_bpermute_b32 v151, v173, v150
	ds_bpermute_b32 v147, v173, v146
	ds_bpermute_b32 v123, v173, v122
	ds_bpermute_b32 v119, v173, v118
	ds_bpermute_b32 v81, v173, v80
	ds_bpermute_b32 v77, v173, v76
	v_lshlrev_b64 v[170:171], 1, v[194:195]
	v_lshl_add_u64 v[170:171], s[10:11], 0, v[170:171]
	s_waitcnt lgkmcnt(0)
	v_add_f32_e32 v168, v168, v169
	v_add_f32_e32 v208, v208, v209
	v_add_f32_e32 v150, v150, v151
	v_add_f32_e32 v146, v146, v147
	v_add_f32_e32 v122, v122, v123
	v_add_f32_e32 v118, v118, v119
	v_add_f32_e32 v80, v80, v81
	v_add_f32_e32 v76, v76, v77
	ds_bpermute_b32 v169, v167, v168
	ds_bpermute_b32 v209, v167, v208
	ds_bpermute_b32 v151, v167, v150
	ds_bpermute_b32 v147, v167, v146
	ds_bpermute_b32 v123, v167, v122
	ds_bpermute_b32 v119, v167, v118
	ds_bpermute_b32 v81, v167, v80
	ds_bpermute_b32 v77, v167, v76
	s_waitcnt lgkmcnt(0)
	v_add_f32_e32 v168, v168, v169
	v_add_f32_e32 v208, v208, v209
	v_add_f32_e32 v150, v150, v151
	v_add_f32_e32 v146, v146, v147
	v_add_f32_e32 v122, v122, v123
	v_add_f32_e32 v118, v118, v119
	v_add_f32_e32 v80, v80, v81
	v_add_f32_e32 v76, v76, v77
	v_mov_b32_e32 v78, 0x358637bd
	v_fma_f32 v168, v168, s22, v78
	v_fma_f32 v208, v208, s22, v78
	v_fma_f32 v150, v150, s22, v78
	v_fma_f32 v146, v146, s22, v78
	v_fma_f32 v122, v122, s22, v78
	v_fma_f32 v118, v118, s22, v78
	v_fma_f32 v80, v80, s22, v78
	v_fma_f32 v76, v76, s22, v78
	v_rsq_f32_e32 v168, v168
	v_rsq_f32_e32 v208, v208
	v_rsq_f32_e32 v150, v150
	v_rsq_f32_e32 v146, v146
	v_rsq_f32_e32 v122, v122
	v_rsq_f32_e32 v118, v118
	v_rsq_f32_e32 v80, v80
	v_rsq_f32_e32 v76, v76
	v_pk_mul_f32 v[142:143], v[142:143], v[168:169] op_sel_hi:[1,0]
	v_pk_mul_f32 v[144:145], v[144:145], v[168:169] op_sel_hi:[1,0]
	v_pk_mul_f32 v[134:135], v[134:135], v[168:169] op_sel_hi:[1,0]
	v_pk_mul_f32 v[136:137], v[136:137], v[168:169] op_sel_hi:[1,0]
	v_mul_f32_e32 v152, 0xbfb8aa3b, v142
	v_mul_f32_e32 v153, 0xbfb8aa3b, v143
	v_mul_f32_e32 v148, 0xbfb8aa3b, v144
	v_mul_f32_e32 v149, 0xbfb8aa3b, v145
	v_mul_f32_e32 v124, 0xbfb8aa3b, v134
	v_mul_f32_e32 v125, 0xbfb8aa3b, v135
	v_mul_f32_e32 v120, 0xbfb8aa3b, v136
	v_mul_f32_e32 v121, 0xbfb8aa3b, v137
	v_pk_mul_f32 v[138:139], v[138:139], v[168:169] op_sel_hi:[1,0]
	v_pk_mul_f32 v[140:141], v[140:141], v[168:169] op_sel_hi:[1,0]
	v_pk_mul_f32 v[130:131], v[130:131], v[168:169] op_sel_hi:[1,0]
	v_pk_mul_f32 v[132:133], v[132:133], v[168:169] op_sel_hi:[1,0]
	v_exp_f32_e32 v152, v152
	v_exp_f32_e32 v153, v153
	v_exp_f32_e32 v148, v148
	v_exp_f32_e32 v149, v149
	v_exp_f32_e32 v124, v124
	v_exp_f32_e32 v125, v125
	v_exp_f32_e32 v120, v120
	v_exp_f32_e32 v121, v121
	v_mad_i64_i32 v[82:83], vcc, v176, s52, v[170:171]
	v_add_f32_e32 v152, 1.0, v152
	v_add_f32_e32 v153, 1.0, v153
	v_add_f32_e32 v148, 1.0, v148
	v_add_f32_e32 v149, 1.0, v149
	v_add_f32_e32 v124, 1.0, v124
	v_add_f32_e32 v125, 1.0, v125
	v_add_f32_e32 v120, 1.0, v120
	v_add_f32_e32 v121, 1.0, v121
	v_rcp_f32_e32 v152, v152
	v_rcp_f32_e32 v153, v153
	v_rcp_f32_e32 v148, v148
	v_rcp_f32_e32 v149, v149
	v_rcp_f32_e32 v124, v124
	v_rcp_f32_e32 v125, v125
	v_rcp_f32_e32 v120, v120
	v_rcp_f32_e32 v121, v121
	s_nop 0
	v_pk_mul_f32 v[142:143], v[142:143], v[152:153]
	v_pk_mul_f32 v[144:145], v[144:145], v[148:149]
	v_pk_mul_f32 v[134:135], v[134:135], v[124:125]
	v_pk_mul_f32 v[136:137], v[136:137], v[120:121]
	v_pk_mul_f32 v[138:139], v[138:139], v[142:143]
	v_pk_mul_f32 v[140:141], v[140:141], v[144:145]
	v_pk_mul_f32 v[130:131], v[130:131], v[134:135]
	v_pk_mul_f32 v[132:133], v[132:133], v[136:137]
	v_cvt_pk_bf16_f32 v138, v138, v139
	v_cvt_pk_bf16_f32 v139, v140, v141
	v_cvt_pk_bf16_f32 v140, v130, v131
	v_cvt_pk_bf16_f32 v141, v132, v133
	global_store_dwordx4 v[82:83], v[138:141], off nt
	v_pk_mul_f32 v[126:127], v[126:127], v[208:209] op_sel_hi:[1,0]
	v_pk_mul_f32 v[128:129], v[128:129], v[208:209] op_sel_hi:[1,0]
	v_pk_mul_f32 v[108:109], v[108:109], v[208:209] op_sel_hi:[1,0]
	v_pk_mul_f32 v[110:111], v[110:111], v[208:209] op_sel_hi:[1,0]
	v_mul_f32_e32 v152, 0xbfb8aa3b, v126
	v_mul_f32_e32 v153, 0xbfb8aa3b, v127
	v_mul_f32_e32 v148, 0xbfb8aa3b, v128
	v_mul_f32_e32 v149, 0xbfb8aa3b, v129
	v_mul_f32_e32 v124, 0xbfb8aa3b, v108
	v_mul_f32_e32 v125, 0xbfb8aa3b, v109
	v_mul_f32_e32 v120, 0xbfb8aa3b, v110
	v_mul_f32_e32 v121, 0xbfb8aa3b, v111
	v_pk_mul_f32 v[114:115], v[114:115], v[208:209] op_sel_hi:[1,0]
	v_pk_mul_f32 v[116:117], v[116:117], v[208:209] op_sel_hi:[1,0]
	v_pk_mul_f32 v[104:105], v[104:105], v[208:209] op_sel_hi:[1,0]
	v_pk_mul_f32 v[106:107], v[106:107], v[208:209] op_sel_hi:[1,0]
	v_exp_f32_e32 v152, v152
	v_exp_f32_e32 v153, v153
	v_exp_f32_e32 v148, v148
	v_exp_f32_e32 v149, v149
	v_exp_f32_e32 v124, v124
	v_exp_f32_e32 v125, v125
	v_exp_f32_e32 v120, v120
	v_exp_f32_e32 v121, v121
	v_mad_i64_i32 v[82:83], vcc, v184, s52, v[170:171]
	v_add_f32_e32 v152, 1.0, v152
	v_add_f32_e32 v153, 1.0, v153
	v_add_f32_e32 v148, 1.0, v148
	v_add_f32_e32 v149, 1.0, v149
	v_add_f32_e32 v124, 1.0, v124
	v_add_f32_e32 v125, 1.0, v125
	v_add_f32_e32 v120, 1.0, v120
	v_add_f32_e32 v121, 1.0, v121
	v_rcp_f32_e32 v152, v152
	v_rcp_f32_e32 v153, v153
	v_rcp_f32_e32 v148, v148
	v_rcp_f32_e32 v149, v149
	v_rcp_f32_e32 v124, v124
	v_rcp_f32_e32 v125, v125
	v_rcp_f32_e32 v120, v120
	v_rcp_f32_e32 v121, v121
	s_nop 0
	v_pk_mul_f32 v[126:127], v[126:127], v[152:153]
	v_pk_mul_f32 v[128:129], v[128:129], v[148:149]
	v_pk_mul_f32 v[108:109], v[108:109], v[124:125]
	v_pk_mul_f32 v[110:111], v[110:111], v[120:121]
	v_pk_mul_f32 v[114:115], v[114:115], v[126:127]
	v_pk_mul_f32 v[116:117], v[116:117], v[128:129]
	v_pk_mul_f32 v[104:105], v[104:105], v[108:109]
	v_pk_mul_f32 v[106:107], v[106:107], v[110:111]
	v_cvt_pk_bf16_f32 v114, v114, v115
	v_cvt_pk_bf16_f32 v115, v116, v117
	v_cvt_pk_bf16_f32 v116, v104, v105
	v_cvt_pk_bf16_f32 v117, v106, v107
	global_store_dwordx4 v[82:83], v[114:117], off nt
	v_pk_mul_f32 v[100:101], v[100:101], v[150:151] op_sel_hi:[1,0]
	v_pk_mul_f32 v[102:103], v[102:103], v[150:151] op_sel_hi:[1,0]
	v_pk_mul_f32 v[92:93], v[92:93], v[150:151] op_sel_hi:[1,0]
	v_pk_mul_f32 v[94:95], v[94:95], v[150:151] op_sel_hi:[1,0]
	v_mul_f32_e32 v152, 0xbfb8aa3b, v100
	v_mul_f32_e32 v153, 0xbfb8aa3b, v101
	v_mul_f32_e32 v148, 0xbfb8aa3b, v102
	v_mul_f32_e32 v149, 0xbfb8aa3b, v103
	v_mul_f32_e32 v124, 0xbfb8aa3b, v92
	v_mul_f32_e32 v125, 0xbfb8aa3b, v93
	v_mul_f32_e32 v120, 0xbfb8aa3b, v94
	v_mul_f32_e32 v121, 0xbfb8aa3b, v95
	v_pk_mul_f32 v[96:97], v[96:97], v[150:151] op_sel_hi:[1,0]
	v_pk_mul_f32 v[98:99], v[98:99], v[150:151] op_sel_hi:[1,0]
	v_pk_mul_f32 v[88:89], v[88:89], v[150:151] op_sel_hi:[1,0]
	v_pk_mul_f32 v[90:91], v[90:91], v[150:151] op_sel_hi:[1,0]
	v_exp_f32_e32 v152, v152
	v_exp_f32_e32 v153, v153
	v_exp_f32_e32 v148, v148
	v_exp_f32_e32 v149, v149
	v_exp_f32_e32 v124, v124
	v_exp_f32_e32 v125, v125
	v_exp_f32_e32 v120, v120
	v_exp_f32_e32 v121, v121
	v_mad_i64_i32 v[82:83], vcc, v182, s52, v[170:171]
	v_add_f32_e32 v152, 1.0, v152
	v_add_f32_e32 v153, 1.0, v153
	v_add_f32_e32 v148, 1.0, v148
	v_add_f32_e32 v149, 1.0, v149
	v_add_f32_e32 v124, 1.0, v124
	v_add_f32_e32 v125, 1.0, v125
	v_add_f32_e32 v120, 1.0, v120
	v_add_f32_e32 v121, 1.0, v121
	v_rcp_f32_e32 v152, v152
	v_rcp_f32_e32 v153, v153
	v_rcp_f32_e32 v148, v148
	v_rcp_f32_e32 v149, v149
	v_rcp_f32_e32 v124, v124
	v_rcp_f32_e32 v125, v125
	v_rcp_f32_e32 v120, v120
	v_rcp_f32_e32 v121, v121
	s_nop 0
	v_pk_mul_f32 v[100:101], v[100:101], v[152:153]
	v_pk_mul_f32 v[102:103], v[102:103], v[148:149]
	v_pk_mul_f32 v[92:93], v[92:93], v[124:125]
	v_pk_mul_f32 v[94:95], v[94:95], v[120:121]
	v_pk_mul_f32 v[96:97], v[96:97], v[100:101]
	v_pk_mul_f32 v[98:99], v[98:99], v[102:103]
	v_pk_mul_f32 v[88:89], v[88:89], v[92:93]
	v_pk_mul_f32 v[90:91], v[90:91], v[94:95]
	v_cvt_pk_bf16_f32 v96, v96, v97
	v_cvt_pk_bf16_f32 v97, v98, v99
	v_cvt_pk_bf16_f32 v98, v88, v89
	v_cvt_pk_bf16_f32 v99, v90, v91
	global_store_dwordx4 v[82:83], v[96:99], off nt
	v_pk_mul_f32 v[84:85], v[84:85], v[146:147] op_sel_hi:[1,0]
	v_pk_mul_f32 v[86:87], v[86:87], v[146:147] op_sel_hi:[1,0]
	v_pk_mul_f32 v[68:69], v[68:69], v[146:147] op_sel_hi:[1,0]
	v_pk_mul_f32 v[70:71], v[70:71], v[146:147] op_sel_hi:[1,0]
	v_mul_f32_e32 v152, 0xbfb8aa3b, v84
	v_mul_f32_e32 v153, 0xbfb8aa3b, v85
	v_mul_f32_e32 v148, 0xbfb8aa3b, v86
	v_mul_f32_e32 v149, 0xbfb8aa3b, v87
	v_mul_f32_e32 v124, 0xbfb8aa3b, v68
	v_mul_f32_e32 v125, 0xbfb8aa3b, v69
	v_mul_f32_e32 v120, 0xbfb8aa3b, v70
	v_mul_f32_e32 v121, 0xbfb8aa3b, v71
	v_pk_mul_f32 v[72:73], v[72:73], v[146:147] op_sel_hi:[1,0]
	v_pk_mul_f32 v[74:75], v[74:75], v[146:147] op_sel_hi:[1,0]
	v_pk_mul_f32 v[64:65], v[64:65], v[146:147] op_sel_hi:[1,0]
	v_pk_mul_f32 v[66:67], v[66:67], v[146:147] op_sel_hi:[1,0]
	v_exp_f32_e32 v152, v152
	v_exp_f32_e32 v153, v153
	v_exp_f32_e32 v148, v148
	v_exp_f32_e32 v149, v149
	v_exp_f32_e32 v124, v124
	v_exp_f32_e32 v125, v125
	v_exp_f32_e32 v120, v120
	v_exp_f32_e32 v121, v121
	v_mad_i64_i32 v[82:83], vcc, v180, s52, v[170:171]
	v_add_f32_e32 v152, 1.0, v152
	v_add_f32_e32 v153, 1.0, v153
	v_add_f32_e32 v148, 1.0, v148
	v_add_f32_e32 v149, 1.0, v149
	v_add_f32_e32 v124, 1.0, v124
	v_add_f32_e32 v125, 1.0, v125
	v_add_f32_e32 v120, 1.0, v120
	v_add_f32_e32 v121, 1.0, v121
	v_rcp_f32_e32 v152, v152
	v_rcp_f32_e32 v153, v153
	v_rcp_f32_e32 v148, v148
	v_rcp_f32_e32 v149, v149
	v_rcp_f32_e32 v124, v124
	v_rcp_f32_e32 v125, v125
	v_rcp_f32_e32 v120, v120
	v_rcp_f32_e32 v121, v121
	s_nop 0
	v_pk_mul_f32 v[84:85], v[84:85], v[152:153]
	v_pk_mul_f32 v[86:87], v[86:87], v[148:149]
	v_pk_mul_f32 v[68:69], v[68:69], v[124:125]
	v_pk_mul_f32 v[70:71], v[70:71], v[120:121]
	v_pk_mul_f32 v[72:73], v[72:73], v[84:85]
	v_pk_mul_f32 v[74:75], v[74:75], v[86:87]
	v_pk_mul_f32 v[64:65], v[64:65], v[68:69]
	v_pk_mul_f32 v[66:67], v[66:67], v[70:71]
	v_cvt_pk_bf16_f32 v72, v72, v73
	v_cvt_pk_bf16_f32 v73, v74, v75
	v_cvt_pk_bf16_f32 v74, v64, v65
	v_cvt_pk_bf16_f32 v75, v66, v67
	global_store_dwordx4 v[82:83], v[72:75], off nt
	v_pk_mul_f32 v[60:61], v[60:61], v[122:123] op_sel_hi:[1,0]
	v_pk_mul_f32 v[62:63], v[62:63], v[122:123] op_sel_hi:[1,0]
	v_pk_mul_f32 v[52:53], v[52:53], v[122:123] op_sel_hi:[1,0]
	v_pk_mul_f32 v[54:55], v[54:55], v[122:123] op_sel_hi:[1,0]
	v_mul_f32_e32 v152, 0xbfb8aa3b, v60
	v_mul_f32_e32 v153, 0xbfb8aa3b, v61
	v_mul_f32_e32 v148, 0xbfb8aa3b, v62
	v_mul_f32_e32 v149, 0xbfb8aa3b, v63
	v_mul_f32_e32 v124, 0xbfb8aa3b, v52
	v_mul_f32_e32 v125, 0xbfb8aa3b, v53
	v_mul_f32_e32 v120, 0xbfb8aa3b, v54
	v_mul_f32_e32 v121, 0xbfb8aa3b, v55
	v_pk_mul_f32 v[56:57], v[56:57], v[122:123] op_sel_hi:[1,0]
	v_pk_mul_f32 v[58:59], v[58:59], v[122:123] op_sel_hi:[1,0]
	v_pk_mul_f32 v[48:49], v[48:49], v[122:123] op_sel_hi:[1,0]
	v_pk_mul_f32 v[50:51], v[50:51], v[122:123] op_sel_hi:[1,0]
	v_exp_f32_e32 v152, v152
	v_exp_f32_e32 v153, v153
	v_exp_f32_e32 v148, v148
	v_exp_f32_e32 v149, v149
	v_exp_f32_e32 v124, v124
	v_exp_f32_e32 v125, v125
	v_exp_f32_e32 v120, v120
	v_exp_f32_e32 v121, v121
	v_mad_i64_i32 v[82:83], vcc, v178, s52, v[170:171]
	v_add_f32_e32 v152, 1.0, v152
	v_add_f32_e32 v153, 1.0, v153
	v_add_f32_e32 v148, 1.0, v148
	v_add_f32_e32 v149, 1.0, v149
	v_add_f32_e32 v124, 1.0, v124
	v_add_f32_e32 v125, 1.0, v125
	v_add_f32_e32 v120, 1.0, v120
	v_add_f32_e32 v121, 1.0, v121
	v_rcp_f32_e32 v152, v152
	v_rcp_f32_e32 v153, v153
	v_rcp_f32_e32 v148, v148
	v_rcp_f32_e32 v149, v149
	v_rcp_f32_e32 v124, v124
	v_rcp_f32_e32 v125, v125
	v_rcp_f32_e32 v120, v120
	v_rcp_f32_e32 v121, v121
	s_nop 0
	v_pk_mul_f32 v[60:61], v[60:61], v[152:153]
	v_pk_mul_f32 v[62:63], v[62:63], v[148:149]
	v_pk_mul_f32 v[52:53], v[52:53], v[124:125]
	v_pk_mul_f32 v[54:55], v[54:55], v[120:121]
	v_pk_mul_f32 v[56:57], v[56:57], v[60:61]
	v_pk_mul_f32 v[58:59], v[58:59], v[62:63]
	v_pk_mul_f32 v[48:49], v[48:49], v[52:53]
	v_pk_mul_f32 v[50:51], v[50:51], v[54:55]
	v_cvt_pk_bf16_f32 v56, v56, v57
	v_cvt_pk_bf16_f32 v57, v58, v59
	v_cvt_pk_bf16_f32 v58, v48, v49
	v_cvt_pk_bf16_f32 v59, v50, v51
	global_store_dwordx4 v[82:83], v[56:59], off nt
	v_pk_mul_f32 v[44:45], v[44:45], v[118:119] op_sel_hi:[1,0]
	v_pk_mul_f32 v[46:47], v[46:47], v[118:119] op_sel_hi:[1,0]
	v_pk_mul_f32 v[36:37], v[36:37], v[118:119] op_sel_hi:[1,0]
	v_pk_mul_f32 v[38:39], v[38:39], v[118:119] op_sel_hi:[1,0]
	v_mul_f32_e32 v152, 0xbfb8aa3b, v44
	v_mul_f32_e32 v153, 0xbfb8aa3b, v45
	v_mul_f32_e32 v148, 0xbfb8aa3b, v46
	v_mul_f32_e32 v149, 0xbfb8aa3b, v47
	v_mul_f32_e32 v124, 0xbfb8aa3b, v36
	v_mul_f32_e32 v125, 0xbfb8aa3b, v37
	v_mul_f32_e32 v120, 0xbfb8aa3b, v38
	v_mul_f32_e32 v121, 0xbfb8aa3b, v39
	v_pk_mul_f32 v[40:41], v[40:41], v[118:119] op_sel_hi:[1,0]
	v_pk_mul_f32 v[42:43], v[42:43], v[118:119] op_sel_hi:[1,0]
	v_pk_mul_f32 v[32:33], v[32:33], v[118:119] op_sel_hi:[1,0]
	v_pk_mul_f32 v[34:35], v[34:35], v[118:119] op_sel_hi:[1,0]
	v_exp_f32_e32 v152, v152
	v_exp_f32_e32 v153, v153
	v_exp_f32_e32 v148, v148
	v_exp_f32_e32 v149, v149
	v_exp_f32_e32 v124, v124
	v_exp_f32_e32 v125, v125
	v_exp_f32_e32 v120, v120
	v_exp_f32_e32 v121, v121
	v_mad_i64_i32 v[82:83], vcc, v174, s52, v[170:171]
	v_add_f32_e32 v152, 1.0, v152
	v_add_f32_e32 v153, 1.0, v153
	v_add_f32_e32 v148, 1.0, v148
	v_add_f32_e32 v149, 1.0, v149
	v_add_f32_e32 v124, 1.0, v124
	v_add_f32_e32 v125, 1.0, v125
	v_add_f32_e32 v120, 1.0, v120
	v_add_f32_e32 v121, 1.0, v121
	v_rcp_f32_e32 v152, v152
	v_rcp_f32_e32 v153, v153
	v_rcp_f32_e32 v148, v148
	v_rcp_f32_e32 v149, v149
	v_rcp_f32_e32 v124, v124
	v_rcp_f32_e32 v125, v125
	v_rcp_f32_e32 v120, v120
	v_rcp_f32_e32 v121, v121
	s_nop 0
	v_pk_mul_f32 v[44:45], v[44:45], v[152:153]
	v_pk_mul_f32 v[46:47], v[46:47], v[148:149]
	v_pk_mul_f32 v[36:37], v[36:37], v[124:125]
	v_pk_mul_f32 v[38:39], v[38:39], v[120:121]
	v_pk_mul_f32 v[40:41], v[40:41], v[44:45]
	v_pk_mul_f32 v[42:43], v[42:43], v[46:47]
	v_pk_mul_f32 v[32:33], v[32:33], v[36:37]
	v_pk_mul_f32 v[34:35], v[34:35], v[38:39]
	v_cvt_pk_bf16_f32 v40, v40, v41
	v_cvt_pk_bf16_f32 v41, v42, v43
	v_cvt_pk_bf16_f32 v42, v32, v33
	v_cvt_pk_bf16_f32 v43, v34, v35
	global_store_dwordx4 v[82:83], v[40:43], off nt
	v_pk_mul_f32 v[28:29], v[28:29], v[80:81] op_sel_hi:[1,0]
	v_pk_mul_f32 v[30:31], v[30:31], v[80:81] op_sel_hi:[1,0]
	v_pk_mul_f32 v[20:21], v[20:21], v[80:81] op_sel_hi:[1,0]
	v_pk_mul_f32 v[22:23], v[22:23], v[80:81] op_sel_hi:[1,0]
	v_mul_f32_e32 v152, 0xbfb8aa3b, v28
	v_mul_f32_e32 v153, 0xbfb8aa3b, v29
	v_mul_f32_e32 v148, 0xbfb8aa3b, v30
	v_mul_f32_e32 v149, 0xbfb8aa3b, v31
	v_mul_f32_e32 v124, 0xbfb8aa3b, v20
	v_mul_f32_e32 v125, 0xbfb8aa3b, v21
	v_mul_f32_e32 v120, 0xbfb8aa3b, v22
	v_mul_f32_e32 v121, 0xbfb8aa3b, v23
	v_pk_mul_f32 v[24:25], v[24:25], v[80:81] op_sel_hi:[1,0]
	v_pk_mul_f32 v[26:27], v[26:27], v[80:81] op_sel_hi:[1,0]
	v_pk_mul_f32 v[16:17], v[16:17], v[80:81] op_sel_hi:[1,0]
	v_pk_mul_f32 v[18:19], v[18:19], v[80:81] op_sel_hi:[1,0]
	v_exp_f32_e32 v152, v152
	v_exp_f32_e32 v153, v153
	v_exp_f32_e32 v148, v148
	v_exp_f32_e32 v149, v149
	v_exp_f32_e32 v124, v124
	v_exp_f32_e32 v125, v125
	v_exp_f32_e32 v120, v120
	v_exp_f32_e32 v121, v121
	v_mad_i64_i32 v[82:83], vcc, v172, s52, v[170:171]
	v_add_f32_e32 v152, 1.0, v152
	v_add_f32_e32 v153, 1.0, v153
	v_add_f32_e32 v148, 1.0, v148
	v_add_f32_e32 v149, 1.0, v149
	v_add_f32_e32 v124, 1.0, v124
	v_add_f32_e32 v125, 1.0, v125
	v_add_f32_e32 v120, 1.0, v120
	v_add_f32_e32 v121, 1.0, v121
	v_rcp_f32_e32 v152, v152
	v_rcp_f32_e32 v153, v153
	v_rcp_f32_e32 v148, v148
	v_rcp_f32_e32 v149, v149
	v_rcp_f32_e32 v124, v124
	v_rcp_f32_e32 v125, v125
	v_rcp_f32_e32 v120, v120
	v_rcp_f32_e32 v121, v121
	s_nop 0
	v_pk_mul_f32 v[28:29], v[28:29], v[152:153]
	v_pk_mul_f32 v[30:31], v[30:31], v[148:149]
	v_pk_mul_f32 v[20:21], v[20:21], v[124:125]
	v_pk_mul_f32 v[22:23], v[22:23], v[120:121]
	v_pk_mul_f32 v[24:25], v[24:25], v[28:29]
	v_pk_mul_f32 v[26:27], v[26:27], v[30:31]
	v_pk_mul_f32 v[16:17], v[16:17], v[20:21]
	v_pk_mul_f32 v[18:19], v[18:19], v[22:23]
	v_cvt_pk_bf16_f32 v24, v24, v25
	v_cvt_pk_bf16_f32 v25, v26, v27
	v_cvt_pk_bf16_f32 v26, v16, v17
	v_cvt_pk_bf16_f32 v27, v18, v19
	global_store_dwordx4 v[82:83], v[24:27], off nt
	v_pk_mul_f32 v[12:13], v[12:13], v[76:77] op_sel_hi:[1,0]
	v_pk_mul_f32 v[14:15], v[14:15], v[76:77] op_sel_hi:[1,0]
	v_pk_mul_f32 v[4:5], v[4:5], v[76:77] op_sel_hi:[1,0]
	v_pk_mul_f32 v[6:7], v[6:7], v[76:77] op_sel_hi:[1,0]
	v_mul_f32_e32 v152, 0xbfb8aa3b, v12
	v_mul_f32_e32 v153, 0xbfb8aa3b, v13
	v_mul_f32_e32 v148, 0xbfb8aa3b, v14
	v_mul_f32_e32 v149, 0xbfb8aa3b, v15
	v_mul_f32_e32 v124, 0xbfb8aa3b, v4
	v_mul_f32_e32 v125, 0xbfb8aa3b, v5
	v_mul_f32_e32 v120, 0xbfb8aa3b, v6
	v_mul_f32_e32 v121, 0xbfb8aa3b, v7
	v_pk_mul_f32 v[8:9], v[8:9], v[76:77] op_sel_hi:[1,0]
	v_pk_mul_f32 v[10:11], v[10:11], v[76:77] op_sel_hi:[1,0]
	v_pk_mul_f32 v[0:1], v[0:1], v[76:77] op_sel_hi:[1,0]
	v_pk_mul_f32 v[2:3], v[2:3], v[76:77] op_sel_hi:[1,0]
	v_exp_f32_e32 v152, v152
	v_exp_f32_e32 v153, v153
	v_exp_f32_e32 v148, v148
	v_exp_f32_e32 v149, v149
	v_exp_f32_e32 v124, v124
	v_exp_f32_e32 v125, v125
	v_exp_f32_e32 v120, v120
	v_exp_f32_e32 v121, v121
	v_mad_i64_i32 v[82:83], vcc, v166, s52, v[170:171]
	v_add_f32_e32 v152, 1.0, v152
	v_add_f32_e32 v153, 1.0, v153
	v_add_f32_e32 v148, 1.0, v148
	v_add_f32_e32 v149, 1.0, v149
	v_add_f32_e32 v124, 1.0, v124
	v_add_f32_e32 v125, 1.0, v125
	v_add_f32_e32 v120, 1.0, v120
	v_add_f32_e32 v121, 1.0, v121
	v_rcp_f32_e32 v152, v152
	v_rcp_f32_e32 v153, v153
	v_rcp_f32_e32 v148, v148
	v_rcp_f32_e32 v149, v149
	v_rcp_f32_e32 v124, v124
	v_rcp_f32_e32 v125, v125
	v_rcp_f32_e32 v120, v120
	v_rcp_f32_e32 v121, v121
	s_nop 0
	v_pk_mul_f32 v[12:13], v[12:13], v[152:153]
	v_pk_mul_f32 v[14:15], v[14:15], v[148:149]
	v_pk_mul_f32 v[4:5], v[4:5], v[124:125]
	v_pk_mul_f32 v[6:7], v[6:7], v[120:121]
	v_pk_mul_f32 v[8:9], v[8:9], v[12:13]
	v_pk_mul_f32 v[10:11], v[10:11], v[14:15]
	v_pk_mul_f32 v[0:1], v[0:1], v[4:5]
	v_pk_mul_f32 v[2:3], v[2:3], v[6:7]
	v_cvt_pk_bf16_f32 v8, v8, v9
	v_cvt_pk_bf16_f32 v9, v10, v11
	v_cvt_pk_bf16_f32 v10, v0, v1
	v_cvt_pk_bf16_f32 v11, v2, v3
	global_store_dwordx4 v[82:83], v[8:11], off nt
	s_andn2_b64 vcc, exec, s[4:5]
	s_mov_b64 s[6:7], -1
	s_cbranch_vccnz .LBB0_272
	s_waitcnt vmcnt(0)
	s_andn2_b64 vcc, exec, s[8:9]
	s_cbranch_vccnz .LBB0_271
	s_barrier
	s_branch .LBB0_271

.LBB0_1474:
	v_lshl_add_u32 v176, s6, 8, v203
	v_ashrrev_i32_e32 v177, 31, v176
	v_lshlrev_b64 v[76:77], 6, v[176:177]
	v_lshl_add_u64 v[76:77], v[160:161], 0, v[76:77]
	v_or_b32_e32 v184, 16, v176
	global_load_dwordx4 v[168:171], v[76:77], off
	v_ashrrev_i32_e32 v185, 31, v184
	v_lshlrev_b64 v[76:77], 6, v[184:185]
	v_lshl_add_u64 v[76:77], v[160:161], 0, v[76:77]
	global_load_dwordx4 v[194:197], v[76:77], off
	v_or_b32_e32 v182, 32, v176
	v_ashrrev_i32_e32 v183, 31, v182
	v_lshlrev_b64 v[76:77], 6, v[182:183]
	v_or_b32_e32 v180, 48, v176
	v_lshl_add_u64 v[76:77], v[160:161], 0, v[76:77]
	v_ashrrev_i32_e32 v181, 31, v180
	global_load_dwordx4 v[150:153], v[76:77], off
	v_lshlrev_b64 v[76:77], 6, v[180:181]
	v_add_u32_e32 v178, 0x80, v176
	v_lshl_add_u64 v[76:77], v[160:161], 0, v[76:77]
	v_ashrrev_i32_e32 v179, 31, v178
	global_load_dwordx4 v[146:149], v[76:77], off
	v_lshlrev_b64 v[76:77], 6, v[178:179]
	v_add_u32_e32 v174, 0x90, v176
	v_lshl_add_u64 v[76:77], v[160:161], 0, v[76:77]
	v_ashrrev_i32_e32 v175, 31, v174
	global_load_dwordx4 v[122:125], v[76:77], off
	v_lshlrev_b64 v[76:77], 6, v[174:175]
	v_add_u32_e32 v172, 0xa0, v176
	v_lshl_add_u64 v[76:77], v[160:161], 0, v[76:77]
	v_ashrrev_i32_e32 v173, 31, v172
	v_lshl_or_b32 v198, s7, 7, v205
	global_load_dwordx4 v[118:121], v[76:77], off
	v_lshlrev_b64 v[76:77], 6, v[172:173]
	v_add_u32_e32 v166, 0xb0, v176
	v_ashrrev_i32_e32 v199, 31, v198
	v_lshl_add_u64 v[76:77], v[160:161], 0, v[76:77]
	v_ashrrev_i32_e32 v167, 31, v166
	v_and_b32_e32 v173, 64, v245
	global_load_dwordx4 v[80:83], v[76:77], off
	v_lshlrev_b64 v[76:77], 6, v[166:167]
	v_xor_b32_e32 v167, 16, v245
	v_add_u32_e32 v175, 64, v173
	v_cmp_lt_i32_e32 vcc, v167, v175
	s_mov_b32 s22, 0x3a800000
	v_lshl_add_u64 v[76:77], v[160:161], 0, v[76:77]
	v_cndmask_b32_e32 v167, v245, v167, vcc
	v_lshlrev_b32_e32 v173, 2, v167
	v_xor_b32_e32 v167, 32, v245
	v_cmp_lt_i32_e32 vcc, v167, v175
	global_load_dwordx4 v[76:79], v[76:77], off
	v_readlane_b32 s50, v255, 34
	v_cndmask_b32_e32 v167, v245, v167, vcc
	v_lshlrev_b32_e32 v167, 2, v167
	v_readlane_b32 s51, v255, 35
	s_waitcnt vmcnt(0)
	v_add_f32_e32 v169, v169, v168
	v_add_f32_e32 v171, v170, v171
	v_add_f32_e32 v195, v195, v194
	v_add_f32_e32 v197, v196, v197
	v_add_f32_e32 v151, v151, v150
	v_add_f32_e32 v153, v152, v153
	v_add_f32_e32 v147, v147, v146
	v_add_f32_e32 v149, v148, v149
	v_add_f32_e32 v123, v123, v122
	v_add_f32_e32 v125, v124, v125
	v_add_f32_e32 v119, v119, v118
	v_add_f32_e32 v121, v120, v121
	v_add_f32_e32 v81, v81, v80
	v_add_f32_e32 v83, v82, v83
	v_add_f32_e32 v77, v77, v76
	v_add_f32_e32 v79, v78, v79
	v_add_f32_e32 v168, v169, v171
	v_add_f32_e32 v194, v195, v197
	v_add_f32_e32 v150, v151, v153
	v_add_f32_e32 v146, v147, v149
	v_add_f32_e32 v122, v123, v125
	v_add_f32_e32 v118, v119, v121
	v_add_f32_e32 v80, v81, v83
	v_add_f32_e32 v76, v77, v79
	ds_bpermute_b32 v169, v173, v168
	ds_bpermute_b32 v195, v173, v194
	ds_bpermute_b32 v151, v173, v150
	ds_bpermute_b32 v147, v173, v146
	ds_bpermute_b32 v123, v173, v122
	ds_bpermute_b32 v119, v173, v118
	ds_bpermute_b32 v81, v173, v80
	ds_bpermute_b32 v77, v173, v76
	v_lshlrev_b64 v[170:171], 1, v[198:199]
	v_lshl_add_u64 v[170:171], s[10:11], 0, v[170:171]
	s_waitcnt lgkmcnt(0)
	v_add_f32_e32 v168, v168, v169
	v_add_f32_e32 v194, v194, v195
	v_add_f32_e32 v150, v150, v151
	v_add_f32_e32 v146, v146, v147
	v_add_f32_e32 v122, v122, v123
	v_add_f32_e32 v118, v118, v119
	v_add_f32_e32 v80, v80, v81
	v_add_f32_e32 v76, v76, v77
	ds_bpermute_b32 v169, v167, v168
	ds_bpermute_b32 v195, v167, v194
	ds_bpermute_b32 v151, v167, v150
	ds_bpermute_b32 v147, v167, v146
	ds_bpermute_b32 v123, v167, v122
	ds_bpermute_b32 v119, v167, v118
	ds_bpermute_b32 v81, v167, v80
	ds_bpermute_b32 v77, v167, v76
	s_waitcnt lgkmcnt(0)
	v_add_f32_e32 v168, v168, v169
	v_add_f32_e32 v194, v194, v195
	v_add_f32_e32 v150, v150, v151
	v_add_f32_e32 v146, v146, v147
	v_add_f32_e32 v122, v122, v123
	v_add_f32_e32 v118, v118, v119
	v_add_f32_e32 v80, v80, v81
	v_add_f32_e32 v76, v76, v77
	v_mov_b32_e32 v78, 0x358637bd
	v_fma_f32 v168, v168, s22, v78
	v_fma_f32 v194, v194, s22, v78
	v_fma_f32 v150, v150, s22, v78
	v_fma_f32 v146, v146, s22, v78
	v_fma_f32 v122, v122, s22, v78
	v_fma_f32 v118, v118, s22, v78
	v_fma_f32 v80, v80, s22, v78
	v_fma_f32 v76, v76, s22, v78
	v_rsq_f32_e32 v168, v168
	v_rsq_f32_e32 v194, v194
	v_rsq_f32_e32 v150, v150
	v_rsq_f32_e32 v146, v146
	v_rsq_f32_e32 v122, v122
	v_rsq_f32_e32 v118, v118
	v_rsq_f32_e32 v80, v80
	v_rsq_f32_e32 v76, v76
	v_pk_mul_f32 v[142:143], v[142:143], v[168:169] op_sel_hi:[1,0]
	v_pk_mul_f32 v[144:145], v[144:145], v[168:169] op_sel_hi:[1,0]
	v_pk_mul_f32 v[134:135], v[134:135], v[168:169] op_sel_hi:[1,0]
	v_pk_mul_f32 v[136:137], v[136:137], v[168:169] op_sel_hi:[1,0]
	v_mul_f32_e32 v152, 0xbfb8aa3b, v142
	v_mul_f32_e32 v153, 0xbfb8aa3b, v143
	v_mul_f32_e32 v148, 0xbfb8aa3b, v144
	v_mul_f32_e32 v149, 0xbfb8aa3b, v145
	v_mul_f32_e32 v124, 0xbfb8aa3b, v134
	v_mul_f32_e32 v125, 0xbfb8aa3b, v135
	v_mul_f32_e32 v120, 0xbfb8aa3b, v136
	v_mul_f32_e32 v121, 0xbfb8aa3b, v137
	v_pk_mul_f32 v[138:139], v[138:139], v[168:169] op_sel_hi:[1,0]
	v_pk_mul_f32 v[140:141], v[140:141], v[168:169] op_sel_hi:[1,0]
	v_pk_mul_f32 v[130:131], v[130:131], v[168:169] op_sel_hi:[1,0]
	v_pk_mul_f32 v[132:133], v[132:133], v[168:169] op_sel_hi:[1,0]
	v_exp_f32_e32 v152, v152
	v_exp_f32_e32 v153, v153
	v_exp_f32_e32 v148, v148
	v_exp_f32_e32 v149, v149
	v_exp_f32_e32 v124, v124
	v_exp_f32_e32 v125, v125
	v_exp_f32_e32 v120, v120
	v_exp_f32_e32 v121, v121
	v_mad_i64_i32 v[82:83], vcc, v176, s52, v[170:171]
	v_add_f32_e32 v152, 1.0, v152
	v_add_f32_e32 v153, 1.0, v153
	v_add_f32_e32 v148, 1.0, v148
	v_add_f32_e32 v149, 1.0, v149
	v_add_f32_e32 v124, 1.0, v124
	v_add_f32_e32 v125, 1.0, v125
	v_add_f32_e32 v120, 1.0, v120
	v_add_f32_e32 v121, 1.0, v121
	v_rcp_f32_e32 v152, v152
	v_rcp_f32_e32 v153, v153
	v_rcp_f32_e32 v148, v148
	v_rcp_f32_e32 v149, v149
	v_rcp_f32_e32 v124, v124
	v_rcp_f32_e32 v125, v125
	v_rcp_f32_e32 v120, v120
	v_rcp_f32_e32 v121, v121
	s_nop 0
	v_pk_mul_f32 v[142:143], v[142:143], v[152:153]
	v_pk_mul_f32 v[144:145], v[144:145], v[148:149]
	v_pk_mul_f32 v[134:135], v[134:135], v[124:125]
	v_pk_mul_f32 v[136:137], v[136:137], v[120:121]
	v_pk_mul_f32 v[138:139], v[138:139], v[142:143]
	v_pk_mul_f32 v[140:141], v[140:141], v[144:145]
	v_pk_mul_f32 v[130:131], v[130:131], v[134:135]
	v_pk_mul_f32 v[132:133], v[132:133], v[136:137]
	v_cvt_pk_bf16_f32 v138, v138, v139
	v_cvt_pk_bf16_f32 v139, v140, v141
	v_cvt_pk_bf16_f32 v140, v130, v131
	v_cvt_pk_bf16_f32 v141, v132, v133
	global_store_dwordx4 v[82:83], v[138:141], off nt
	v_pk_mul_f32 v[126:127], v[126:127], v[194:195] op_sel_hi:[1,0]
	v_pk_mul_f32 v[128:129], v[128:129], v[194:195] op_sel_hi:[1,0]
	v_pk_mul_f32 v[108:109], v[108:109], v[194:195] op_sel_hi:[1,0]
	v_pk_mul_f32 v[110:111], v[110:111], v[194:195] op_sel_hi:[1,0]
	v_mul_f32_e32 v152, 0xbfb8aa3b, v126
	v_mul_f32_e32 v153, 0xbfb8aa3b, v127
	v_mul_f32_e32 v148, 0xbfb8aa3b, v128
	v_mul_f32_e32 v149, 0xbfb8aa3b, v129
	v_mul_f32_e32 v124, 0xbfb8aa3b, v108
	v_mul_f32_e32 v125, 0xbfb8aa3b, v109
	v_mul_f32_e32 v120, 0xbfb8aa3b, v110
	v_mul_f32_e32 v121, 0xbfb8aa3b, v111
	v_pk_mul_f32 v[114:115], v[114:115], v[194:195] op_sel_hi:[1,0]
	v_pk_mul_f32 v[116:117], v[116:117], v[194:195] op_sel_hi:[1,0]
	v_pk_mul_f32 v[104:105], v[104:105], v[194:195] op_sel_hi:[1,0]
	v_pk_mul_f32 v[106:107], v[106:107], v[194:195] op_sel_hi:[1,0]
	v_exp_f32_e32 v152, v152
	v_exp_f32_e32 v153, v153
	v_exp_f32_e32 v148, v148
	v_exp_f32_e32 v149, v149
	v_exp_f32_e32 v124, v124
	v_exp_f32_e32 v125, v125
	v_exp_f32_e32 v120, v120
	v_exp_f32_e32 v121, v121
	v_mad_i64_i32 v[82:83], vcc, v184, s52, v[170:171]
	v_add_f32_e32 v152, 1.0, v152
	v_add_f32_e32 v153, 1.0, v153
	v_add_f32_e32 v148, 1.0, v148
	v_add_f32_e32 v149, 1.0, v149
	v_add_f32_e32 v124, 1.0, v124
	v_add_f32_e32 v125, 1.0, v125
	v_add_f32_e32 v120, 1.0, v120
	v_add_f32_e32 v121, 1.0, v121
	v_rcp_f32_e32 v152, v152
	v_rcp_f32_e32 v153, v153
	v_rcp_f32_e32 v148, v148
	v_rcp_f32_e32 v149, v149
	v_rcp_f32_e32 v124, v124
	v_rcp_f32_e32 v125, v125
	v_rcp_f32_e32 v120, v120
	v_rcp_f32_e32 v121, v121
	s_nop 0
	v_pk_mul_f32 v[126:127], v[126:127], v[152:153]
	v_pk_mul_f32 v[128:129], v[128:129], v[148:149]
	v_pk_mul_f32 v[108:109], v[108:109], v[124:125]
	v_pk_mul_f32 v[110:111], v[110:111], v[120:121]
	v_pk_mul_f32 v[114:115], v[114:115], v[126:127]
	v_pk_mul_f32 v[116:117], v[116:117], v[128:129]
	v_pk_mul_f32 v[104:105], v[104:105], v[108:109]
	v_pk_mul_f32 v[106:107], v[106:107], v[110:111]
	v_cvt_pk_bf16_f32 v114, v114, v115
	v_cvt_pk_bf16_f32 v115, v116, v117
	v_cvt_pk_bf16_f32 v116, v104, v105
	v_cvt_pk_bf16_f32 v117, v106, v107
	global_store_dwordx4 v[82:83], v[114:117], off nt
	v_pk_mul_f32 v[100:101], v[100:101], v[150:151] op_sel_hi:[1,0]
	v_pk_mul_f32 v[102:103], v[102:103], v[150:151] op_sel_hi:[1,0]
	v_pk_mul_f32 v[92:93], v[92:93], v[150:151] op_sel_hi:[1,0]
	v_pk_mul_f32 v[94:95], v[94:95], v[150:151] op_sel_hi:[1,0]
	v_mul_f32_e32 v152, 0xbfb8aa3b, v100
	v_mul_f32_e32 v153, 0xbfb8aa3b, v101
	v_mul_f32_e32 v148, 0xbfb8aa3b, v102
	v_mul_f32_e32 v149, 0xbfb8aa3b, v103
	v_mul_f32_e32 v124, 0xbfb8aa3b, v92
	v_mul_f32_e32 v125, 0xbfb8aa3b, v93
	v_mul_f32_e32 v120, 0xbfb8aa3b, v94
	v_mul_f32_e32 v121, 0xbfb8aa3b, v95
	v_pk_mul_f32 v[96:97], v[96:97], v[150:151] op_sel_hi:[1,0]
	v_pk_mul_f32 v[98:99], v[98:99], v[150:151] op_sel_hi:[1,0]
	v_pk_mul_f32 v[88:89], v[88:89], v[150:151] op_sel_hi:[1,0]
	v_pk_mul_f32 v[90:91], v[90:91], v[150:151] op_sel_hi:[1,0]
	v_exp_f32_e32 v152, v152
	v_exp_f32_e32 v153, v153
	v_exp_f32_e32 v148, v148
	v_exp_f32_e32 v149, v149
	v_exp_f32_e32 v124, v124
	v_exp_f32_e32 v125, v125
	v_exp_f32_e32 v120, v120
	v_exp_f32_e32 v121, v121
	v_mad_i64_i32 v[82:83], vcc, v182, s52, v[170:171]
	v_add_f32_e32 v152, 1.0, v152
	v_add_f32_e32 v153, 1.0, v153
	v_add_f32_e32 v148, 1.0, v148
	v_add_f32_e32 v149, 1.0, v149
	v_add_f32_e32 v124, 1.0, v124
	v_add_f32_e32 v125, 1.0, v125
	v_add_f32_e32 v120, 1.0, v120
	v_add_f32_e32 v121, 1.0, v121
	v_rcp_f32_e32 v152, v152
	v_rcp_f32_e32 v153, v153
	v_rcp_f32_e32 v148, v148
	v_rcp_f32_e32 v149, v149
	v_rcp_f32_e32 v124, v124
	v_rcp_f32_e32 v125, v125
	v_rcp_f32_e32 v120, v120
	v_rcp_f32_e32 v121, v121
	s_nop 0
	v_pk_mul_f32 v[100:101], v[100:101], v[152:153]
	v_pk_mul_f32 v[102:103], v[102:103], v[148:149]
	v_pk_mul_f32 v[92:93], v[92:93], v[124:125]
	v_pk_mul_f32 v[94:95], v[94:95], v[120:121]
	v_pk_mul_f32 v[96:97], v[96:97], v[100:101]
	v_pk_mul_f32 v[98:99], v[98:99], v[102:103]
	v_pk_mul_f32 v[88:89], v[88:89], v[92:93]
	v_pk_mul_f32 v[90:91], v[90:91], v[94:95]
	v_cvt_pk_bf16_f32 v96, v96, v97
	v_cvt_pk_bf16_f32 v97, v98, v99
	v_cvt_pk_bf16_f32 v98, v88, v89
	v_cvt_pk_bf16_f32 v99, v90, v91
	global_store_dwordx4 v[82:83], v[96:99], off nt
	v_pk_mul_f32 v[84:85], v[84:85], v[146:147] op_sel_hi:[1,0]
	v_pk_mul_f32 v[86:87], v[86:87], v[146:147] op_sel_hi:[1,0]
	v_pk_mul_f32 v[68:69], v[68:69], v[146:147] op_sel_hi:[1,0]
	v_pk_mul_f32 v[70:71], v[70:71], v[146:147] op_sel_hi:[1,0]
	v_mul_f32_e32 v152, 0xbfb8aa3b, v84
	v_mul_f32_e32 v153, 0xbfb8aa3b, v85
	v_mul_f32_e32 v148, 0xbfb8aa3b, v86
	v_mul_f32_e32 v149, 0xbfb8aa3b, v87
	v_mul_f32_e32 v124, 0xbfb8aa3b, v68
	v_mul_f32_e32 v125, 0xbfb8aa3b, v69
	v_mul_f32_e32 v120, 0xbfb8aa3b, v70
	v_mul_f32_e32 v121, 0xbfb8aa3b, v71
	v_pk_mul_f32 v[72:73], v[72:73], v[146:147] op_sel_hi:[1,0]
	v_pk_mul_f32 v[74:75], v[74:75], v[146:147] op_sel_hi:[1,0]
	v_pk_mul_f32 v[64:65], v[64:65], v[146:147] op_sel_hi:[1,0]
	v_pk_mul_f32 v[66:67], v[66:67], v[146:147] op_sel_hi:[1,0]
	v_exp_f32_e32 v152, v152
	v_exp_f32_e32 v153, v153
	v_exp_f32_e32 v148, v148
	v_exp_f32_e32 v149, v149
	v_exp_f32_e32 v124, v124
	v_exp_f32_e32 v125, v125
	v_exp_f32_e32 v120, v120
	v_exp_f32_e32 v121, v121
	v_mad_i64_i32 v[82:83], vcc, v180, s52, v[170:171]
	v_add_f32_e32 v152, 1.0, v152
	v_add_f32_e32 v153, 1.0, v153
	v_add_f32_e32 v148, 1.0, v148
	v_add_f32_e32 v149, 1.0, v149
	v_add_f32_e32 v124, 1.0, v124
	v_add_f32_e32 v125, 1.0, v125
	v_add_f32_e32 v120, 1.0, v120
	v_add_f32_e32 v121, 1.0, v121
	v_rcp_f32_e32 v152, v152
	v_rcp_f32_e32 v153, v153
	v_rcp_f32_e32 v148, v148
	v_rcp_f32_e32 v149, v149
	v_rcp_f32_e32 v124, v124
	v_rcp_f32_e32 v125, v125
	v_rcp_f32_e32 v120, v120
	v_rcp_f32_e32 v121, v121
	s_nop 0
	v_pk_mul_f32 v[84:85], v[84:85], v[152:153]
	v_pk_mul_f32 v[86:87], v[86:87], v[148:149]
	v_pk_mul_f32 v[68:69], v[68:69], v[124:125]
	v_pk_mul_f32 v[70:71], v[70:71], v[120:121]
	v_pk_mul_f32 v[72:73], v[72:73], v[84:85]
	v_pk_mul_f32 v[74:75], v[74:75], v[86:87]
	v_pk_mul_f32 v[64:65], v[64:65], v[68:69]
	v_pk_mul_f32 v[66:67], v[66:67], v[70:71]
	v_cvt_pk_bf16_f32 v72, v72, v73
	v_cvt_pk_bf16_f32 v73, v74, v75
	v_cvt_pk_bf16_f32 v74, v64, v65
	v_cvt_pk_bf16_f32 v75, v66, v67
	global_store_dwordx4 v[82:83], v[72:75], off nt
	v_pk_mul_f32 v[60:61], v[60:61], v[122:123] op_sel_hi:[1,0]
	v_pk_mul_f32 v[62:63], v[62:63], v[122:123] op_sel_hi:[1,0]
	v_pk_mul_f32 v[52:53], v[52:53], v[122:123] op_sel_hi:[1,0]
	v_pk_mul_f32 v[54:55], v[54:55], v[122:123] op_sel_hi:[1,0]
	v_mul_f32_e32 v152, 0xbfb8aa3b, v60
	v_mul_f32_e32 v153, 0xbfb8aa3b, v61
	v_mul_f32_e32 v148, 0xbfb8aa3b, v62
	v_mul_f32_e32 v149, 0xbfb8aa3b, v63
	v_mul_f32_e32 v124, 0xbfb8aa3b, v52
	v_mul_f32_e32 v125, 0xbfb8aa3b, v53
	v_mul_f32_e32 v120, 0xbfb8aa3b, v54
	v_mul_f32_e32 v121, 0xbfb8aa3b, v55
	v_pk_mul_f32 v[56:57], v[56:57], v[122:123] op_sel_hi:[1,0]
	v_pk_mul_f32 v[58:59], v[58:59], v[122:123] op_sel_hi:[1,0]
	v_pk_mul_f32 v[48:49], v[48:49], v[122:123] op_sel_hi:[1,0]
	v_pk_mul_f32 v[50:51], v[50:51], v[122:123] op_sel_hi:[1,0]
	v_exp_f32_e32 v152, v152
	v_exp_f32_e32 v153, v153
	v_exp_f32_e32 v148, v148
	v_exp_f32_e32 v149, v149
	v_exp_f32_e32 v124, v124
	v_exp_f32_e32 v125, v125
	v_exp_f32_e32 v120, v120
	v_exp_f32_e32 v121, v121
	v_mad_i64_i32 v[82:83], vcc, v178, s52, v[170:171]
	v_add_f32_e32 v152, 1.0, v152
	v_add_f32_e32 v153, 1.0, v153
	v_add_f32_e32 v148, 1.0, v148
	v_add_f32_e32 v149, 1.0, v149
	v_add_f32_e32 v124, 1.0, v124
	v_add_f32_e32 v125, 1.0, v125
	v_add_f32_e32 v120, 1.0, v120
	v_add_f32_e32 v121, 1.0, v121
	v_rcp_f32_e32 v152, v152
	v_rcp_f32_e32 v153, v153
	v_rcp_f32_e32 v148, v148
	v_rcp_f32_e32 v149, v149
	v_rcp_f32_e32 v124, v124
	v_rcp_f32_e32 v125, v125
	v_rcp_f32_e32 v120, v120
	v_rcp_f32_e32 v121, v121
	s_nop 0
	v_pk_mul_f32 v[60:61], v[60:61], v[152:153]
	v_pk_mul_f32 v[62:63], v[62:63], v[148:149]
	v_pk_mul_f32 v[52:53], v[52:53], v[124:125]
	v_pk_mul_f32 v[54:55], v[54:55], v[120:121]
	v_pk_mul_f32 v[56:57], v[56:57], v[60:61]
	v_pk_mul_f32 v[58:59], v[58:59], v[62:63]
	v_pk_mul_f32 v[48:49], v[48:49], v[52:53]
	v_pk_mul_f32 v[50:51], v[50:51], v[54:55]
	v_cvt_pk_bf16_f32 v56, v56, v57
	v_cvt_pk_bf16_f32 v57, v58, v59
	v_cvt_pk_bf16_f32 v58, v48, v49
	v_cvt_pk_bf16_f32 v59, v50, v51
	global_store_dwordx4 v[82:83], v[56:59], off nt
	v_pk_mul_f32 v[44:45], v[44:45], v[118:119] op_sel_hi:[1,0]
	v_pk_mul_f32 v[46:47], v[46:47], v[118:119] op_sel_hi:[1,0]
	v_pk_mul_f32 v[36:37], v[36:37], v[118:119] op_sel_hi:[1,0]
	v_pk_mul_f32 v[38:39], v[38:39], v[118:119] op_sel_hi:[1,0]
	v_mul_f32_e32 v152, 0xbfb8aa3b, v44
	v_mul_f32_e32 v153, 0xbfb8aa3b, v45
	v_mul_f32_e32 v148, 0xbfb8aa3b, v46
	v_mul_f32_e32 v149, 0xbfb8aa3b, v47
	v_mul_f32_e32 v124, 0xbfb8aa3b, v36
	v_mul_f32_e32 v125, 0xbfb8aa3b, v37
	v_mul_f32_e32 v120, 0xbfb8aa3b, v38
	v_mul_f32_e32 v121, 0xbfb8aa3b, v39
	v_pk_mul_f32 v[40:41], v[40:41], v[118:119] op_sel_hi:[1,0]
	v_pk_mul_f32 v[42:43], v[42:43], v[118:119] op_sel_hi:[1,0]
	v_pk_mul_f32 v[32:33], v[32:33], v[118:119] op_sel_hi:[1,0]
	v_pk_mul_f32 v[34:35], v[34:35], v[118:119] op_sel_hi:[1,0]
	v_exp_f32_e32 v152, v152
	v_exp_f32_e32 v153, v153
	v_exp_f32_e32 v148, v148
	v_exp_f32_e32 v149, v149
	v_exp_f32_e32 v124, v124
	v_exp_f32_e32 v125, v125
	v_exp_f32_e32 v120, v120
	v_exp_f32_e32 v121, v121
	v_mad_i64_i32 v[82:83], vcc, v174, s52, v[170:171]
	v_add_f32_e32 v152, 1.0, v152
	v_add_f32_e32 v153, 1.0, v153
	v_add_f32_e32 v148, 1.0, v148
	v_add_f32_e32 v149, 1.0, v149
	v_add_f32_e32 v124, 1.0, v124
	v_add_f32_e32 v125, 1.0, v125
	v_add_f32_e32 v120, 1.0, v120
	v_add_f32_e32 v121, 1.0, v121
	v_rcp_f32_e32 v152, v152
	v_rcp_f32_e32 v153, v153
	v_rcp_f32_e32 v148, v148
	v_rcp_f32_e32 v149, v149
	v_rcp_f32_e32 v124, v124
	v_rcp_f32_e32 v125, v125
	v_rcp_f32_e32 v120, v120
	v_rcp_f32_e32 v121, v121
	s_nop 0
	v_pk_mul_f32 v[44:45], v[44:45], v[152:153]
	v_pk_mul_f32 v[46:47], v[46:47], v[148:149]
	v_pk_mul_f32 v[36:37], v[36:37], v[124:125]
	v_pk_mul_f32 v[38:39], v[38:39], v[120:121]
	v_pk_mul_f32 v[40:41], v[40:41], v[44:45]
	v_pk_mul_f32 v[42:43], v[42:43], v[46:47]
	v_pk_mul_f32 v[32:33], v[32:33], v[36:37]
	v_pk_mul_f32 v[34:35], v[34:35], v[38:39]
	v_cvt_pk_bf16_f32 v40, v40, v41
	v_cvt_pk_bf16_f32 v41, v42, v43
	v_cvt_pk_bf16_f32 v42, v32, v33
	v_cvt_pk_bf16_f32 v43, v34, v35
	global_store_dwordx4 v[82:83], v[40:43], off nt
	v_pk_mul_f32 v[28:29], v[28:29], v[80:81] op_sel_hi:[1,0]
	v_pk_mul_f32 v[30:31], v[30:31], v[80:81] op_sel_hi:[1,0]
	v_pk_mul_f32 v[20:21], v[20:21], v[80:81] op_sel_hi:[1,0]
	v_pk_mul_f32 v[22:23], v[22:23], v[80:81] op_sel_hi:[1,0]
	v_mul_f32_e32 v152, 0xbfb8aa3b, v28
	v_mul_f32_e32 v153, 0xbfb8aa3b, v29
	v_mul_f32_e32 v148, 0xbfb8aa3b, v30
	v_mul_f32_e32 v149, 0xbfb8aa3b, v31
	v_mul_f32_e32 v124, 0xbfb8aa3b, v20
	v_mul_f32_e32 v125, 0xbfb8aa3b, v21
	v_mul_f32_e32 v120, 0xbfb8aa3b, v22
	v_mul_f32_e32 v121, 0xbfb8aa3b, v23
	v_pk_mul_f32 v[24:25], v[24:25], v[80:81] op_sel_hi:[1,0]
	v_pk_mul_f32 v[26:27], v[26:27], v[80:81] op_sel_hi:[1,0]
	v_pk_mul_f32 v[16:17], v[16:17], v[80:81] op_sel_hi:[1,0]
	v_pk_mul_f32 v[18:19], v[18:19], v[80:81] op_sel_hi:[1,0]
	v_exp_f32_e32 v152, v152
	v_exp_f32_e32 v153, v153
	v_exp_f32_e32 v148, v148
	v_exp_f32_e32 v149, v149
	v_exp_f32_e32 v124, v124
	v_exp_f32_e32 v125, v125
	v_exp_f32_e32 v120, v120
	v_exp_f32_e32 v121, v121
	v_mad_i64_i32 v[82:83], vcc, v172, s52, v[170:171]
	v_add_f32_e32 v152, 1.0, v152
	v_add_f32_e32 v153, 1.0, v153
	v_add_f32_e32 v148, 1.0, v148
	v_add_f32_e32 v149, 1.0, v149
	v_add_f32_e32 v124, 1.0, v124
	v_add_f32_e32 v125, 1.0, v125
	v_add_f32_e32 v120, 1.0, v120
	v_add_f32_e32 v121, 1.0, v121
	v_rcp_f32_e32 v152, v152
	v_rcp_f32_e32 v153, v153
	v_rcp_f32_e32 v148, v148
	v_rcp_f32_e32 v149, v149
	v_rcp_f32_e32 v124, v124
	v_rcp_f32_e32 v125, v125
	v_rcp_f32_e32 v120, v120
	v_rcp_f32_e32 v121, v121
	s_nop 0
	v_pk_mul_f32 v[28:29], v[28:29], v[152:153]
	v_pk_mul_f32 v[30:31], v[30:31], v[148:149]
	v_pk_mul_f32 v[20:21], v[20:21], v[124:125]
	v_pk_mul_f32 v[22:23], v[22:23], v[120:121]
	v_pk_mul_f32 v[24:25], v[24:25], v[28:29]
	v_pk_mul_f32 v[26:27], v[26:27], v[30:31]
	v_pk_mul_f32 v[16:17], v[16:17], v[20:21]
	v_pk_mul_f32 v[18:19], v[18:19], v[22:23]
	v_cvt_pk_bf16_f32 v24, v24, v25
	v_cvt_pk_bf16_f32 v25, v26, v27
	v_cvt_pk_bf16_f32 v26, v16, v17
	v_cvt_pk_bf16_f32 v27, v18, v19
	global_store_dwordx4 v[82:83], v[24:27], off nt
	v_pk_mul_f32 v[12:13], v[12:13], v[76:77] op_sel_hi:[1,0]
	v_pk_mul_f32 v[14:15], v[14:15], v[76:77] op_sel_hi:[1,0]
	v_pk_mul_f32 v[4:5], v[4:5], v[76:77] op_sel_hi:[1,0]
	v_pk_mul_f32 v[6:7], v[6:7], v[76:77] op_sel_hi:[1,0]
	v_mul_f32_e32 v152, 0xbfb8aa3b, v12
	v_mul_f32_e32 v153, 0xbfb8aa3b, v13
	v_mul_f32_e32 v148, 0xbfb8aa3b, v14
	v_mul_f32_e32 v149, 0xbfb8aa3b, v15
	v_mul_f32_e32 v124, 0xbfb8aa3b, v4
	v_mul_f32_e32 v125, 0xbfb8aa3b, v5
	v_mul_f32_e32 v120, 0xbfb8aa3b, v6
	v_mul_f32_e32 v121, 0xbfb8aa3b, v7
	v_pk_mul_f32 v[8:9], v[8:9], v[76:77] op_sel_hi:[1,0]
	v_pk_mul_f32 v[10:11], v[10:11], v[76:77] op_sel_hi:[1,0]
	v_pk_mul_f32 v[0:1], v[0:1], v[76:77] op_sel_hi:[1,0]
	v_pk_mul_f32 v[2:3], v[2:3], v[76:77] op_sel_hi:[1,0]
	v_exp_f32_e32 v152, v152
	v_exp_f32_e32 v153, v153
	v_exp_f32_e32 v148, v148
	v_exp_f32_e32 v149, v149
	v_exp_f32_e32 v124, v124
	v_exp_f32_e32 v125, v125
	v_exp_f32_e32 v120, v120
	v_exp_f32_e32 v121, v121
	v_mad_i64_i32 v[82:83], vcc, v166, s52, v[170:171]
	v_add_f32_e32 v152, 1.0, v152
	v_add_f32_e32 v153, 1.0, v153
	v_add_f32_e32 v148, 1.0, v148
	v_add_f32_e32 v149, 1.0, v149
	v_add_f32_e32 v124, 1.0, v124
	v_add_f32_e32 v125, 1.0, v125
	v_add_f32_e32 v120, 1.0, v120
	v_add_f32_e32 v121, 1.0, v121
	v_rcp_f32_e32 v152, v152
	v_rcp_f32_e32 v153, v153
	v_rcp_f32_e32 v148, v148
	v_rcp_f32_e32 v149, v149
	v_rcp_f32_e32 v124, v124
	v_rcp_f32_e32 v125, v125
	v_rcp_f32_e32 v120, v120
	v_rcp_f32_e32 v121, v121
	s_nop 0
	v_pk_mul_f32 v[12:13], v[12:13], v[152:153]
	v_pk_mul_f32 v[14:15], v[14:15], v[148:149]
	v_pk_mul_f32 v[4:5], v[4:5], v[124:125]
	v_pk_mul_f32 v[6:7], v[6:7], v[120:121]
	v_pk_mul_f32 v[8:9], v[8:9], v[12:13]
	v_pk_mul_f32 v[10:11], v[10:11], v[14:15]
	v_pk_mul_f32 v[0:1], v[0:1], v[4:5]
	v_pk_mul_f32 v[2:3], v[2:3], v[6:7]
	v_cvt_pk_bf16_f32 v8, v8, v9
	v_cvt_pk_bf16_f32 v9, v10, v11
	v_cvt_pk_bf16_f32 v10, v0, v1
	v_cvt_pk_bf16_f32 v11, v2, v3
	global_store_dwordx4 v[82:83], v[8:11], off nt
	s_andn2_b64 vcc, exec, s[4:5]
	s_mov_b64 s[6:7], -1
	s_cbranch_vccnz .LBB0_1467
	s_waitcnt vmcnt(0)
	s_andn2_b64 vcc, exec, s[8:9]
	s_cbranch_vccnz .LBB0_1466
	s_barrier
	s_branch .LBB0_1466
